# layer 1: post-norm + gated residual fused into the w_out GEMM epilogue (row sums of squares exchanged between the 8 column tiles of a row block, f32 z round trip and post phase removed)
# speedup vs baseline: 1.0084x; 1.0076x over previous
.LBB0_1165:
	s_or_b64 exec, exec, s[0:1]
	s_cmp_eq_u32 s3, 3
	s_cbranch_scc1 .Lgo_fz_epi
	s_cmp_eq_u32 s3, 0
	s_cbranch_scc1 .Lgo_sk_epi
	s_load_dwordx2 s[94:95], s[88:89], 0x168
	s_load_dwordx2 s[98:99], s[88:89], 0x170
	v_lshrrev_b32_e32 v170, 6, v167
	v_and_b32_e32 v171, 63, v167
	v_lshlrev_b32_e32 v170, 15, v170
	v_lshl_add_u32 v170, v171, 4, v170
	s_lshl_b32 s2, s32, 18
	s_lshl_b32 s32, s32, 2
	s_add_u32 s32, s32, 0x180
	v_mov_b32_e32 v171, s32
	v_readfirstlane_b32 s32, v167
	s_waitcnt lgkmcnt(0)
	s_add_u32 s94, s94, s2
	s_addc_u32 s95, s95, 0
	s_cmp_eq_u32 s3, 2
	s_cbranch_scc0 .Lgo_sk_fin
	s_nop 7
	s_nop 7
	global_store_dwordx4 v170, v[0:3], s[94:95] sc0 sc1
	global_store_dwordx4 v170, v[4:7], s[94:95] offset:1024 sc0 sc1
	global_store_dwordx4 v170, v[8:11], s[94:95] offset:2048 sc0 sc1
	global_store_dwordx4 v170, v[12:15], s[94:95] offset:3072 sc0 sc1
	v_add_u32_e32 v170, 0x1000, v170
	global_store_dwordx4 v170, v[16:19], s[94:95] sc0 sc1
	global_store_dwordx4 v170, v[20:23], s[94:95] offset:1024 sc0 sc1
	global_store_dwordx4 v170, v[24:27], s[94:95] offset:2048 sc0 sc1
	global_store_dwordx4 v170, v[28:31], s[94:95] offset:3072 sc0 sc1
	v_add_u32_e32 v170, 0x1000, v170
	global_store_dwordx4 v170, v[32:35], s[94:95] sc0 sc1
	global_store_dwordx4 v170, v[36:39], s[94:95] offset:1024 sc0 sc1
	global_store_dwordx4 v170, v[40:43], s[94:95] offset:2048 sc0 sc1
	global_store_dwordx4 v170, v[44:47], s[94:95] offset:3072 sc0 sc1
	v_add_u32_e32 v170, 0x1000, v170
	global_store_dwordx4 v170, v[48:51], s[94:95] sc0 sc1
	global_store_dwordx4 v170, v[52:55], s[94:95] offset:1024 sc0 sc1
	global_store_dwordx4 v170, v[56:59], s[94:95] offset:2048 sc0 sc1
	global_store_dwordx4 v170, v[60:63], s[94:95] offset:3072 sc0 sc1
	v_add_u32_e32 v170, 0x1000, v170
	global_store_dwordx4 v170, v[64:67], s[94:95] sc0 sc1
	global_store_dwordx4 v170, v[68:71], s[94:95] offset:1024 sc0 sc1
	global_store_dwordx4 v170, v[72:75], s[94:95] offset:2048 sc0 sc1
	global_store_dwordx4 v170, v[76:79], s[94:95] offset:3072 sc0 sc1
	v_add_u32_e32 v170, 0x1000, v170
	global_store_dwordx4 v170, v[80:83], s[94:95] sc0 sc1
	global_store_dwordx4 v170, v[84:87], s[94:95] offset:1024 sc0 sc1
	global_store_dwordx4 v170, v[88:91], s[94:95] offset:2048 sc0 sc1
	global_store_dwordx4 v170, v[92:95], s[94:95] offset:3072 sc0 sc1
	v_add_u32_e32 v170, 0x1000, v170
	global_store_dwordx4 v170, v[96:99], s[94:95] sc0 sc1
	global_store_dwordx4 v170, v[100:103], s[94:95] offset:1024 sc0 sc1
	global_store_dwordx4 v170, v[104:107], s[94:95] offset:2048 sc0 sc1
	global_store_dwordx4 v170, v[108:111], s[94:95] offset:3072 sc0 sc1
	v_add_u32_e32 v170, 0x1000, v170
	global_store_dwordx4 v170, v[112:115], s[94:95] sc0 sc1
	global_store_dwordx4 v170, v[116:119], s[94:95] offset:1024 sc0 sc1
	global_store_dwordx4 v170, v[120:123], s[94:95] offset:2048 sc0 sc1
	global_store_dwordx4 v170, v[124:127], s[94:95] offset:3072 sc0 sc1
	v_add_u32_e32 v170, 0x1000, v170
	s_waitcnt vmcnt(0)
	s_barrier
	s_cmp_lt_u32 s32, 64
	s_cbranch_scc0 .Lgo_sk_pend
	s_mov_b64 exec, 1
	v_mov_b32_e32 v172, 1
	global_atomic_add v171, v172, s[98:99]
	s_waitcnt vmcnt(0)
	s_mov_b64 exec, -1

.Lgo_sk_epi:
	v_mov_b32_e32 v129, v167
	v_readlane_b32 s0, v254, 1
	v_ashrrev_i32_e32 v128, 2, v129
	v_and_b32_e32 v130, 15, v129
	v_and_b32_e32 v128, 0xffffffc0, v128
	v_lshrrev_b32_e32 v131, 2, v129
	v_lshrrev_b32_e32 v129, 1, v129
	v_add_u32_e32 v128, s36, v128
	v_and_b32_e32 v129, 0x60, v129
	v_and_or_b32 v128, v131, 12, v128
	v_or3_b32 v130, v130, v129, s34
	v_ashrrev_i32_e32 v131, 31, v130
	v_ashrrev_i32_e32 v129, 31, v128
	v_or_b32_e32 v134, 1, v128
	v_lshl_add_u64 v[130:131], v[130:131], 2, s[26:27]
	v_lshlrev_b64 v[132:133], 13, v[128:129]
	v_ashrrev_i32_e32 v135, 31, v134
	v_lshl_add_u64 v[132:133], v[130:131], 0, v[132:133]
	v_lshlrev_b64 v[134:135], 13, v[134:135]
	global_store_dword v[132:133], v124, off
	v_lshl_add_u64 v[134:135], v[130:131], 0, v[134:135]
	v_or_b32_e32 v124, 2, v128
	v_or_b32_e32 v136, 3, v128
	global_store_dword v[134:135], v125, off
	v_ashrrev_i32_e32 v125, 31, v124
	v_ashrrev_i32_e32 v137, 31, v136
	v_lshlrev_b64 v[124:125], 13, v[124:125]
	v_lshlrev_b64 v[136:137], 13, v[136:137]
	v_lshl_add_u64 v[124:125], v[130:131], 0, v[124:125]
	v_lshl_add_u64 v[136:137], v[130:131], 0, v[136:137]
	global_store_dword v[124:125], v126, off
	global_store_dword v[136:137], v127, off
	global_store_dword v[132:133], v120, off offset:64
	global_store_dword v[134:135], v121, off offset:64
	global_store_dword v[124:125], v122, off offset:64
	global_store_dword v[136:137], v123, off offset:64
	v_or_b32_e32 v120, 16, v128
	v_ashrrev_i32_e32 v121, 31, v120
	v_or_b32_e32 v122, 17, v128
	v_lshlrev_b64 v[120:121], 13, v[120:121]
	v_ashrrev_i32_e32 v123, 31, v122
	v_lshl_add_u64 v[120:121], v[130:131], 0, v[120:121]
	v_lshlrev_b64 v[122:123], 13, v[122:123]
	global_store_dword v[120:121], v116, off
	v_lshl_add_u64 v[122:123], v[130:131], 0, v[122:123]
	v_or_b32_e32 v116, 18, v128
	v_or_b32_e32 v126, 19, v128
	global_store_dword v[122:123], v117, off
	v_ashrrev_i32_e32 v117, 31, v116
	v_ashrrev_i32_e32 v127, 31, v126
	v_lshlrev_b64 v[116:117], 13, v[116:117]
	v_lshlrev_b64 v[126:127], 13, v[126:127]
	v_lshl_add_u64 v[116:117], v[130:131], 0, v[116:117]
	v_lshl_add_u64 v[126:127], v[130:131], 0, v[126:127]
	global_store_dword v[116:117], v118, off
	global_store_dword v[126:127], v119, off
	global_store_dword v[120:121], v112, off offset:64
	global_store_dword v[122:123], v113, off offset:64
	global_store_dword v[116:117], v114, off offset:64
	global_store_dword v[126:127], v115, off offset:64
	v_or_b32_e32 v112, 32, v128
	v_ashrrev_i32_e32 v113, 31, v112
	v_or_b32_e32 v114, 33, v128
	v_lshlrev_b64 v[112:113], 13, v[112:113]
	v_ashrrev_i32_e32 v115, 31, v114
	v_lshl_add_u64 v[112:113], v[130:131], 0, v[112:113]
	v_lshlrev_b64 v[114:115], 13, v[114:115]
	global_store_dword v[112:113], v108, off
	v_lshl_add_u64 v[114:115], v[130:131], 0, v[114:115]
	v_or_b32_e32 v108, 34, v128
	v_or_b32_e32 v118, 35, v128
	global_store_dword v[114:115], v109, off
	v_ashrrev_i32_e32 v109, 31, v108
	v_ashrrev_i32_e32 v119, 31, v118
	v_lshlrev_b64 v[108:109], 13, v[108:109]
	v_lshlrev_b64 v[118:119], 13, v[118:119]
	v_lshl_add_u64 v[108:109], v[130:131], 0, v[108:109]
	v_lshl_add_u64 v[118:119], v[130:131], 0, v[118:119]
	global_store_dword v[108:109], v110, off
	global_store_dword v[118:119], v111, off
	global_store_dword v[112:113], v104, off offset:64
	global_store_dword v[114:115], v105, off offset:64
	global_store_dword v[108:109], v106, off offset:64
	global_store_dword v[118:119], v107, off offset:64
	v_or_b32_e32 v104, 48, v128
	v_ashrrev_i32_e32 v105, 31, v104
	v_or_b32_e32 v106, 49, v128
	v_lshlrev_b64 v[104:105], 13, v[104:105]
	v_ashrrev_i32_e32 v107, 31, v106
	v_lshl_add_u64 v[104:105], v[130:131], 0, v[104:105]
	v_lshlrev_b64 v[106:107], 13, v[106:107]
	global_store_dword v[104:105], v84, off
	v_lshl_add_u64 v[106:107], v[130:131], 0, v[106:107]
	v_or_b32_e32 v84, 50, v128
	v_or_b32_e32 v110, 51, v128
	global_store_dword v[106:107], v85, off
	v_ashrrev_i32_e32 v85, 31, v84
	v_ashrrev_i32_e32 v111, 31, v110
	v_lshlrev_b64 v[84:85], 13, v[84:85]
	v_lshlrev_b64 v[110:111], 13, v[110:111]
	v_lshl_add_u64 v[84:85], v[130:131], 0, v[84:85]
	v_lshl_add_u64 v[110:111], v[130:131], 0, v[110:111]
	global_store_dword v[84:85], v86, off
	global_store_dword v[110:111], v87, off
	global_store_dword v[104:105], v76, off offset:64
	global_store_dword v[106:107], v77, off offset:64
	global_store_dword v[84:85], v78, off offset:64
	global_store_dword v[110:111], v79, off offset:64
	global_store_dword v[132:133], v100, off offset:512
	global_store_dword v[134:135], v101, off offset:512
	global_store_dword v[124:125], v102, off offset:512
	global_store_dword v[136:137], v103, off offset:512
	global_store_dword v[132:133], v96, off offset:576
	global_store_dword v[134:135], v97, off offset:576
	global_store_dword v[124:125], v98, off offset:576
	global_store_dword v[136:137], v99, off offset:576
	global_store_dword v[120:121], v92, off offset:512
	global_store_dword v[122:123], v93, off offset:512
	global_store_dword v[116:117], v94, off offset:512
	global_store_dword v[126:127], v95, off offset:512
	global_store_dword v[120:121], v88, off offset:576
	global_store_dword v[122:123], v89, off offset:576
	global_store_dword v[116:117], v90, off offset:576
	global_store_dword v[126:127], v91, off offset:576
	global_store_dword v[112:113], v80, off offset:512
	global_store_dword v[114:115], v81, off offset:512
	global_store_dword v[108:109], v82, off offset:512
	global_store_dword v[118:119], v83, off offset:512
	global_store_dword v[112:113], v72, off offset:576
	global_store_dword v[114:115], v73, off offset:576
	global_store_dword v[108:109], v74, off offset:576
	global_store_dword v[118:119], v75, off offset:576
	global_store_dword v[104:105], v68, off offset:512
	global_store_dword v[106:107], v69, off offset:512
	global_store_dword v[84:85], v70, off offset:512
	global_store_dword v[110:111], v71, off offset:512
	global_store_dword v[104:105], v64, off offset:576
	global_store_dword v[106:107], v65, off offset:576
	global_store_dword v[84:85], v66, off offset:576
	global_store_dword v[110:111], v67, off offset:576
	v_add_u32_e32 v64, 0x80, v128
	v_ashrrev_i32_e32 v65, 31, v64
	v_add_u32_e32 v66, 0x81, v128
	v_lshlrev_b64 v[64:65], 13, v[64:65]
	v_ashrrev_i32_e32 v67, 31, v66
	v_lshl_add_u64 v[64:65], v[130:131], 0, v[64:65]
	v_lshlrev_b64 v[66:67], 13, v[66:67]
	global_store_dword v[64:65], v60, off
	v_lshl_add_u64 v[66:67], v[130:131], 0, v[66:67]
	v_add_u32_e32 v60, 0x82, v128
	v_add_u32_e32 v68, 0x83, v128
	global_store_dword v[66:67], v61, off
	v_ashrrev_i32_e32 v61, 31, v60
	v_ashrrev_i32_e32 v69, 31, v68
	v_lshlrev_b64 v[60:61], 13, v[60:61]
	v_lshlrev_b64 v[68:69], 13, v[68:69]
	v_lshl_add_u64 v[60:61], v[130:131], 0, v[60:61]
	v_lshl_add_u64 v[68:69], v[130:131], 0, v[68:69]
	global_store_dword v[60:61], v62, off
	global_store_dword v[68:69], v63, off
	global_store_dword v[64:65], v56, off offset:64
	global_store_dword v[66:67], v57, off offset:64
	global_store_dword v[60:61], v58, off offset:64
	global_store_dword v[68:69], v59, off offset:64
	v_add_u32_e32 v56, 0x90, v128
	v_ashrrev_i32_e32 v57, 31, v56
	v_add_u32_e32 v58, 0x91, v128
	v_lshlrev_b64 v[56:57], 13, v[56:57]
	v_ashrrev_i32_e32 v59, 31, v58
	v_lshl_add_u64 v[56:57], v[130:131], 0, v[56:57]
	v_lshlrev_b64 v[58:59], 13, v[58:59]
	global_store_dword v[56:57], v52, off
	v_lshl_add_u64 v[58:59], v[130:131], 0, v[58:59]
	v_add_u32_e32 v52, 0x92, v128
	v_add_u32_e32 v62, 0x93, v128
	global_store_dword v[58:59], v53, off
	v_ashrrev_i32_e32 v53, 31, v52
	v_ashrrev_i32_e32 v63, 31, v62
	v_lshlrev_b64 v[52:53], 13, v[52:53]
	v_lshlrev_b64 v[62:63], 13, v[62:63]
	v_lshl_add_u64 v[52:53], v[130:131], 0, v[52:53]
	v_lshl_add_u64 v[62:63], v[130:131], 0, v[62:63]
	global_store_dword v[52:53], v54, off
	global_store_dword v[62:63], v55, off
	global_store_dword v[56:57], v48, off offset:64
	global_store_dword v[58:59], v49, off offset:64
	global_store_dword v[52:53], v50, off offset:64
	global_store_dword v[62:63], v51, off offset:64
	v_add_u32_e32 v48, 0xa0, v128
	v_ashrrev_i32_e32 v49, 31, v48
	v_add_u32_e32 v50, 0xa1, v128
	v_lshlrev_b64 v[48:49], 13, v[48:49]
	v_ashrrev_i32_e32 v51, 31, v50
	v_lshl_add_u64 v[48:49], v[130:131], 0, v[48:49]
	v_lshlrev_b64 v[50:51], 13, v[50:51]
	global_store_dword v[48:49], v44, off
	v_lshl_add_u64 v[50:51], v[130:131], 0, v[50:51]
	v_add_u32_e32 v44, 0xa2, v128
	v_add_u32_e32 v54, 0xa3, v128
	global_store_dword v[50:51], v45, off
	v_ashrrev_i32_e32 v45, 31, v44
	v_ashrrev_i32_e32 v55, 31, v54
	v_lshlrev_b64 v[44:45], 13, v[44:45]
	v_lshlrev_b64 v[54:55], 13, v[54:55]
	v_lshl_add_u64 v[44:45], v[130:131], 0, v[44:45]
	v_lshl_add_u64 v[54:55], v[130:131], 0, v[54:55]
	global_store_dword v[44:45], v46, off
	global_store_dword v[54:55], v47, off
	global_store_dword v[48:49], v40, off offset:64
	global_store_dword v[50:51], v41, off offset:64
	global_store_dword v[44:45], v42, off offset:64
	global_store_dword v[54:55], v43, off offset:64
	v_add_u32_e32 v40, 0xb0, v128
	v_ashrrev_i32_e32 v41, 31, v40
	v_add_u32_e32 v42, 0xb1, v128
	v_lshlrev_b64 v[40:41], 13, v[40:41]
	v_ashrrev_i32_e32 v43, 31, v42
	v_lshl_add_u64 v[40:41], v[130:131], 0, v[40:41]
	v_lshlrev_b64 v[42:43], 13, v[42:43]
	global_store_dword v[40:41], v36, off
	v_lshl_add_u64 v[42:43], v[130:131], 0, v[42:43]
	v_add_u32_e32 v36, 0xb2, v128
	v_add_u32_e32 v46, 0xb3, v128
	global_store_dword v[42:43], v37, off
	v_ashrrev_i32_e32 v37, 31, v36
	v_ashrrev_i32_e32 v47, 31, v46
	v_lshlrev_b64 v[36:37], 13, v[36:37]
	v_lshlrev_b64 v[46:47], 13, v[46:47]
	s_add_i32 s44, s44, s0
	v_lshl_add_u64 v[36:37], v[130:131], 0, v[36:37]
	v_lshl_add_u64 v[46:47], v[130:131], 0, v[46:47]
	s_cmp_ge_i32 s44, s46
	global_store_dword v[36:37], v38, off
	global_store_dword v[46:47], v39, off
	global_store_dword v[40:41], v28, off offset:64
	global_store_dword v[42:43], v29, off offset:64
	global_store_dword v[36:37], v30, off offset:64
	global_store_dword v[46:47], v31, off offset:64
	global_store_dword v[64:65], v32, off offset:512
	global_store_dword v[66:67], v33, off offset:512
	global_store_dword v[60:61], v34, off offset:512
	global_store_dword v[68:69], v35, off offset:512
	global_store_dword v[64:65], v24, off offset:576
	global_store_dword v[66:67], v25, off offset:576
	global_store_dword v[60:61], v26, off offset:576
	global_store_dword v[68:69], v27, off offset:576
	global_store_dword v[56:57], v20, off offset:512
	global_store_dword v[58:59], v21, off offset:512
	global_store_dword v[52:53], v22, off offset:512
	global_store_dword v[62:63], v23, off offset:512
	global_store_dword v[56:57], v16, off offset:576
	global_store_dword v[58:59], v17, off offset:576
	global_store_dword v[52:53], v18, off offset:576
	global_store_dword v[62:63], v19, off offset:576
	global_store_dword v[48:49], v12, off offset:512
	global_store_dword v[50:51], v13, off offset:512
	global_store_dword v[44:45], v14, off offset:512
	global_store_dword v[54:55], v15, off offset:512
	global_store_dword v[48:49], v8, off offset:576
	global_store_dword v[50:51], v9, off offset:576
	global_store_dword v[44:45], v10, off offset:576
	global_store_dword v[54:55], v11, off offset:576
	global_store_dword v[40:41], v4, off offset:512
	global_store_dword v[42:43], v5, off offset:512
	global_store_dword v[36:37], v6, off offset:512
	global_store_dword v[46:47], v7, off offset:512
	global_store_dword v[40:41], v0, off offset:576
	global_store_dword v[42:43], v1, off offset:576
	global_store_dword v[36:37], v2, off offset:576
	global_store_dword v[46:47], v3, off offset:576
	s_barrier
	v_readlane_b32 s1, v254, 2
	s_cbranch_scc1 .LBB0_1172
	s_branch .LBB0_1166
.Lgo_fz_epi:
	s_nop 7
	s_nop 7
	s_load_dwordx2 s[94:95], s[88:89], 0x168
	s_load_dwordx2 s[98:99], s[88:89], 0x170
	v_and_b32_e32 v160, 15, v167
	v_bfe_u32 v161, v167, 4, 2
	v_bfe_u32 v162, v167, 6, 2
	v_lshrrev_b32_e32 v163, 8, v167
	v_lshlrev_b32_e32 v163, 6, v163
	v_lshl_add_u32 v163, v161, 2, v163
	v_lshl_add_u32 v164, v162, 5, v160
	v_mul_f32_e32 v194, v124, v124
	v_fmac_f32_e32 v194, v120, v120
	v_fmac_f32_e32 v194, v100, v100
	v_fmac_f32_e32 v194, v96, v96
	v_mul_f32_e32 v195, v125, v125
	v_fmac_f32_e32 v195, v121, v121
	v_fmac_f32_e32 v195, v101, v101
	v_fmac_f32_e32 v195, v97, v97
	v_mul_f32_e32 v196, v126, v126
	v_fmac_f32_e32 v196, v122, v122
	v_fmac_f32_e32 v196, v102, v102
	v_fmac_f32_e32 v196, v98, v98
	v_mul_f32_e32 v197, v127, v127
	v_fmac_f32_e32 v197, v123, v123
	v_fmac_f32_e32 v197, v103, v103
	v_fmac_f32_e32 v197, v99, v99
	v_mul_f32_e32 v198, v116, v116
	v_fmac_f32_e32 v198, v112, v112
	v_fmac_f32_e32 v198, v92, v92
	v_fmac_f32_e32 v198, v88, v88
	v_mul_f32_e32 v199, v117, v117
	v_fmac_f32_e32 v199, v113, v113
	v_fmac_f32_e32 v199, v93, v93
	v_fmac_f32_e32 v199, v89, v89
	v_mul_f32_e32 v200, v118, v118
	v_fmac_f32_e32 v200, v114, v114
	v_fmac_f32_e32 v200, v94, v94
	v_fmac_f32_e32 v200, v90, v90
	v_mul_f32_e32 v201, v119, v119
	v_fmac_f32_e32 v201, v115, v115
	v_fmac_f32_e32 v201, v95, v95
	v_fmac_f32_e32 v201, v91, v91
	v_mul_f32_e32 v202, v108, v108
	v_fmac_f32_e32 v202, v104, v104
	v_fmac_f32_e32 v202, v80, v80
	v_fmac_f32_e32 v202, v72, v72
	v_mul_f32_e32 v203, v109, v109
	v_fmac_f32_e32 v203, v105, v105
	v_fmac_f32_e32 v203, v81, v81
	v_fmac_f32_e32 v203, v73, v73
	v_mul_f32_e32 v204, v110, v110
	v_fmac_f32_e32 v204, v106, v106
	v_fmac_f32_e32 v204, v82, v82
	v_fmac_f32_e32 v204, v74, v74
	v_mul_f32_e32 v205, v111, v111
	v_fmac_f32_e32 v205, v107, v107
	v_fmac_f32_e32 v205, v83, v83
	v_fmac_f32_e32 v205, v75, v75
	v_mul_f32_e32 v206, v84, v84
	v_fmac_f32_e32 v206, v76, v76
	v_fmac_f32_e32 v206, v68, v68
	v_fmac_f32_e32 v206, v64, v64
	v_mul_f32_e32 v207, v85, v85
	v_fmac_f32_e32 v207, v77, v77
	v_fmac_f32_e32 v207, v69, v69
	v_fmac_f32_e32 v207, v65, v65
	v_mul_f32_e32 v208, v86, v86
	v_fmac_f32_e32 v208, v78, v78
	v_fmac_f32_e32 v208, v70, v70
	v_fmac_f32_e32 v208, v66, v66
	v_mul_f32_e32 v209, v87, v87
	v_fmac_f32_e32 v209, v79, v79
	v_fmac_f32_e32 v209, v71, v71
	v_fmac_f32_e32 v209, v67, v67
	v_mul_f32_e32 v210, v60, v60
	v_fmac_f32_e32 v210, v56, v56
	v_fmac_f32_e32 v210, v32, v32
	v_fmac_f32_e32 v210, v24, v24
	v_mul_f32_e32 v211, v61, v61
	v_fmac_f32_e32 v211, v57, v57
	v_fmac_f32_e32 v211, v33, v33
	v_fmac_f32_e32 v211, v25, v25
	v_mul_f32_e32 v212, v62, v62
	v_fmac_f32_e32 v212, v58, v58
	v_fmac_f32_e32 v212, v34, v34
	v_fmac_f32_e32 v212, v26, v26
	v_mul_f32_e32 v213, v63, v63
	v_fmac_f32_e32 v213, v59, v59
	v_fmac_f32_e32 v213, v35, v35
	v_fmac_f32_e32 v213, v27, v27
	v_mul_f32_e32 v214, v52, v52
	v_fmac_f32_e32 v214, v48, v48
	v_fmac_f32_e32 v214, v20, v20
	v_fmac_f32_e32 v214, v16, v16
	v_mul_f32_e32 v215, v53, v53
	v_fmac_f32_e32 v215, v49, v49
	v_fmac_f32_e32 v215, v21, v21
	v_fmac_f32_e32 v215, v17, v17
	v_mul_f32_e32 v216, v54, v54
	v_fmac_f32_e32 v216, v50, v50
	v_fmac_f32_e32 v216, v22, v22
	v_fmac_f32_e32 v216, v18, v18
	v_mul_f32_e32 v217, v55, v55
	v_fmac_f32_e32 v217, v51, v51
	v_fmac_f32_e32 v217, v23, v23
	v_fmac_f32_e32 v217, v19, v19
	v_mul_f32_e32 v218, v44, v44
	v_fmac_f32_e32 v218, v40, v40
	v_fmac_f32_e32 v218, v12, v12
	v_fmac_f32_e32 v218, v8, v8
	v_mul_f32_e32 v219, v45, v45
	v_fmac_f32_e32 v219, v41, v41
	v_fmac_f32_e32 v219, v13, v13
	v_fmac_f32_e32 v219, v9, v9
	v_mul_f32_e32 v220, v46, v46
	v_fmac_f32_e32 v220, v42, v42
	v_fmac_f32_e32 v220, v14, v14
	v_fmac_f32_e32 v220, v10, v10
	v_mul_f32_e32 v221, v47, v47
	v_fmac_f32_e32 v221, v43, v43
	v_fmac_f32_e32 v221, v15, v15
	v_fmac_f32_e32 v221, v11, v11
	v_mul_f32_e32 v222, v36, v36
	v_fmac_f32_e32 v222, v28, v28
	v_fmac_f32_e32 v222, v4, v4
	v_fmac_f32_e32 v222, v0, v0
	v_mul_f32_e32 v223, v37, v37
	v_fmac_f32_e32 v223, v29, v29
	v_fmac_f32_e32 v223, v5, v5
	v_fmac_f32_e32 v223, v1, v1
	v_mul_f32_e32 v224, v38, v38
	v_fmac_f32_e32 v224, v30, v30
	v_fmac_f32_e32 v224, v6, v6
	v_fmac_f32_e32 v224, v2, v2
	v_mul_f32_e32 v225, v39, v39
	v_fmac_f32_e32 v225, v31, v31
	v_fmac_f32_e32 v225, v7, v7
	v_fmac_f32_e32 v225, v3, v3
	s_nop 1
	v_add_f32_dpp v194, v194, v194 row_ror:8 row_mask:0xf bank_mask:0xf
	v_add_f32_dpp v195, v195, v195 row_ror:8 row_mask:0xf bank_mask:0xf
	v_add_f32_dpp v196, v196, v196 row_ror:8 row_mask:0xf bank_mask:0xf
	v_add_f32_dpp v197, v197, v197 row_ror:8 row_mask:0xf bank_mask:0xf
	v_add_f32_dpp v198, v198, v198 row_ror:8 row_mask:0xf bank_mask:0xf
	v_add_f32_dpp v199, v199, v199 row_ror:8 row_mask:0xf bank_mask:0xf
	v_add_f32_dpp v200, v200, v200 row_ror:8 row_mask:0xf bank_mask:0xf
	v_add_f32_dpp v201, v201, v201 row_ror:8 row_mask:0xf bank_mask:0xf
	v_add_f32_dpp v202, v202, v202 row_ror:8 row_mask:0xf bank_mask:0xf
	v_add_f32_dpp v203, v203, v203 row_ror:8 row_mask:0xf bank_mask:0xf
	v_add_f32_dpp v204, v204, v204 row_ror:8 row_mask:0xf bank_mask:0xf
	v_add_f32_dpp v205, v205, v205 row_ror:8 row_mask:0xf bank_mask:0xf
	v_add_f32_dpp v206, v206, v206 row_ror:8 row_mask:0xf bank_mask:0xf
	v_add_f32_dpp v207, v207, v207 row_ror:8 row_mask:0xf bank_mask:0xf
	v_add_f32_dpp v208, v208, v208 row_ror:8 row_mask:0xf bank_mask:0xf
	v_add_f32_dpp v209, v209, v209 row_ror:8 row_mask:0xf bank_mask:0xf
	v_add_f32_dpp v210, v210, v210 row_ror:8 row_mask:0xf bank_mask:0xf
	v_add_f32_dpp v211, v211, v211 row_ror:8 row_mask:0xf bank_mask:0xf
	v_add_f32_dpp v212, v212, v212 row_ror:8 row_mask:0xf bank_mask:0xf
	v_add_f32_dpp v213, v213, v213 row_ror:8 row_mask:0xf bank_mask:0xf
	v_add_f32_dpp v214, v214, v214 row_ror:8 row_mask:0xf bank_mask:0xf
	v_add_f32_dpp v215, v215, v215 row_ror:8 row_mask:0xf bank_mask:0xf
	v_add_f32_dpp v216, v216, v216 row_ror:8 row_mask:0xf bank_mask:0xf
	v_add_f32_dpp v217, v217, v217 row_ror:8 row_mask:0xf bank_mask:0xf
	v_add_f32_dpp v218, v218, v218 row_ror:8 row_mask:0xf bank_mask:0xf
	v_add_f32_dpp v219, v219, v219 row_ror:8 row_mask:0xf bank_mask:0xf
	v_add_f32_dpp v220, v220, v220 row_ror:8 row_mask:0xf bank_mask:0xf
	v_add_f32_dpp v221, v221, v221 row_ror:8 row_mask:0xf bank_mask:0xf
	v_add_f32_dpp v222, v222, v222 row_ror:8 row_mask:0xf bank_mask:0xf
	v_add_f32_dpp v223, v223, v223 row_ror:8 row_mask:0xf bank_mask:0xf
	v_add_f32_dpp v224, v224, v224 row_ror:8 row_mask:0xf bank_mask:0xf
	v_add_f32_dpp v225, v225, v225 row_ror:8 row_mask:0xf bank_mask:0xf
	s_nop 1
	v_add_f32_dpp v194, v194, v194 row_ror:4 row_mask:0xf bank_mask:0xf
	v_add_f32_dpp v195, v195, v195 row_ror:4 row_mask:0xf bank_mask:0xf
	v_add_f32_dpp v196, v196, v196 row_ror:4 row_mask:0xf bank_mask:0xf
	v_add_f32_dpp v197, v197, v197 row_ror:4 row_mask:0xf bank_mask:0xf
	v_add_f32_dpp v198, v198, v198 row_ror:4 row_mask:0xf bank_mask:0xf
	v_add_f32_dpp v199, v199, v199 row_ror:4 row_mask:0xf bank_mask:0xf
	v_add_f32_dpp v200, v200, v200 row_ror:4 row_mask:0xf bank_mask:0xf
	v_add_f32_dpp v201, v201, v201 row_ror:4 row_mask:0xf bank_mask:0xf
	v_add_f32_dpp v202, v202, v202 row_ror:4 row_mask:0xf bank_mask:0xf
	v_add_f32_dpp v203, v203, v203 row_ror:4 row_mask:0xf bank_mask:0xf
	v_add_f32_dpp v204, v204, v204 row_ror:4 row_mask:0xf bank_mask:0xf
	v_add_f32_dpp v205, v205, v205 row_ror:4 row_mask:0xf bank_mask:0xf
	v_add_f32_dpp v206, v206, v206 row_ror:4 row_mask:0xf bank_mask:0xf
	v_add_f32_dpp v207, v207, v207 row_ror:4 row_mask:0xf bank_mask:0xf
	v_add_f32_dpp v208, v208, v208 row_ror:4 row_mask:0xf bank_mask:0xf
	v_add_f32_dpp v209, v209, v209 row_ror:4 row_mask:0xf bank_mask:0xf
	v_add_f32_dpp v210, v210, v210 row_ror:4 row_mask:0xf bank_mask:0xf
	v_add_f32_dpp v211, v211, v211 row_ror:4 row_mask:0xf bank_mask:0xf
	v_add_f32_dpp v212, v212, v212 row_ror:4 row_mask:0xf bank_mask:0xf
	v_add_f32_dpp v213, v213, v213 row_ror:4 row_mask:0xf bank_mask:0xf
	v_add_f32_dpp v214, v214, v214 row_ror:4 row_mask:0xf bank_mask:0xf
	v_add_f32_dpp v215, v215, v215 row_ror:4 row_mask:0xf bank_mask:0xf
	v_add_f32_dpp v216, v216, v216 row_ror:4 row_mask:0xf bank_mask:0xf
	v_add_f32_dpp v217, v217, v217 row_ror:4 row_mask:0xf bank_mask:0xf
	v_add_f32_dpp v218, v218, v218 row_ror:4 row_mask:0xf bank_mask:0xf
	v_add_f32_dpp v219, v219, v219 row_ror:4 row_mask:0xf bank_mask:0xf
	v_add_f32_dpp v220, v220, v220 row_ror:4 row_mask:0xf bank_mask:0xf
	v_add_f32_dpp v221, v221, v221 row_ror:4 row_mask:0xf bank_mask:0xf
	v_add_f32_dpp v222, v222, v222 row_ror:4 row_mask:0xf bank_mask:0xf
	v_add_f32_dpp v223, v223, v223 row_ror:4 row_mask:0xf bank_mask:0xf
	v_add_f32_dpp v224, v224, v224 row_ror:4 row_mask:0xf bank_mask:0xf
	v_add_f32_dpp v225, v225, v225 row_ror:4 row_mask:0xf bank_mask:0xf
	s_nop 1
	v_add_f32_dpp v194, v194, v194 row_ror:2 row_mask:0xf bank_mask:0xf
	v_add_f32_dpp v195, v195, v195 row_ror:2 row_mask:0xf bank_mask:0xf
	v_add_f32_dpp v196, v196, v196 row_ror:2 row_mask:0xf bank_mask:0xf
	v_add_f32_dpp v197, v197, v197 row_ror:2 row_mask:0xf bank_mask:0xf
	v_add_f32_dpp v198, v198, v198 row_ror:2 row_mask:0xf bank_mask:0xf
	v_add_f32_dpp v199, v199, v199 row_ror:2 row_mask:0xf bank_mask:0xf
	v_add_f32_dpp v200, v200, v200 row_ror:2 row_mask:0xf bank_mask:0xf
	v_add_f32_dpp v201, v201, v201 row_ror:2 row_mask:0xf bank_mask:0xf
	v_add_f32_dpp v202, v202, v202 row_ror:2 row_mask:0xf bank_mask:0xf
	v_add_f32_dpp v203, v203, v203 row_ror:2 row_mask:0xf bank_mask:0xf
	v_add_f32_dpp v204, v204, v204 row_ror:2 row_mask:0xf bank_mask:0xf
	v_add_f32_dpp v205, v205, v205 row_ror:2 row_mask:0xf bank_mask:0xf
	v_add_f32_dpp v206, v206, v206 row_ror:2 row_mask:0xf bank_mask:0xf
	v_add_f32_dpp v207, v207, v207 row_ror:2 row_mask:0xf bank_mask:0xf
	v_add_f32_dpp v208, v208, v208 row_ror:2 row_mask:0xf bank_mask:0xf
	v_add_f32_dpp v209, v209, v209 row_ror:2 row_mask:0xf bank_mask:0xf
	v_add_f32_dpp v210, v210, v210 row_ror:2 row_mask:0xf bank_mask:0xf
	v_add_f32_dpp v211, v211, v211 row_ror:2 row_mask:0xf bank_mask:0xf
	v_add_f32_dpp v212, v212, v212 row_ror:2 row_mask:0xf bank_mask:0xf
	v_add_f32_dpp v213, v213, v213 row_ror:2 row_mask:0xf bank_mask:0xf
	v_add_f32_dpp v214, v214, v214 row_ror:2 row_mask:0xf bank_mask:0xf
	v_add_f32_dpp v215, v215, v215 row_ror:2 row_mask:0xf bank_mask:0xf
	v_add_f32_dpp v216, v216, v216 row_ror:2 row_mask:0xf bank_mask:0xf
	v_add_f32_dpp v217, v217, v217 row_ror:2 row_mask:0xf bank_mask:0xf
	v_add_f32_dpp v218, v218, v218 row_ror:2 row_mask:0xf bank_mask:0xf
	v_add_f32_dpp v219, v219, v219 row_ror:2 row_mask:0xf bank_mask:0xf
	v_add_f32_dpp v220, v220, v220 row_ror:2 row_mask:0xf bank_mask:0xf
	v_add_f32_dpp v221, v221, v221 row_ror:2 row_mask:0xf bank_mask:0xf
	v_add_f32_dpp v222, v222, v222 row_ror:2 row_mask:0xf bank_mask:0xf
	v_add_f32_dpp v223, v223, v223 row_ror:2 row_mask:0xf bank_mask:0xf
	v_add_f32_dpp v224, v224, v224 row_ror:2 row_mask:0xf bank_mask:0xf
	v_add_f32_dpp v225, v225, v225 row_ror:2 row_mask:0xf bank_mask:0xf
	s_nop 1
	v_add_f32_dpp v194, v194, v194 row_ror:1 row_mask:0xf bank_mask:0xf
	v_add_f32_dpp v195, v195, v195 row_ror:1 row_mask:0xf bank_mask:0xf
	v_add_f32_dpp v196, v196, v196 row_ror:1 row_mask:0xf bank_mask:0xf
	v_add_f32_dpp v197, v197, v197 row_ror:1 row_mask:0xf bank_mask:0xf
	v_add_f32_dpp v198, v198, v198 row_ror:1 row_mask:0xf bank_mask:0xf
	v_add_f32_dpp v199, v199, v199 row_ror:1 row_mask:0xf bank_mask:0xf
	v_add_f32_dpp v200, v200, v200 row_ror:1 row_mask:0xf bank_mask:0xf
	v_add_f32_dpp v201, v201, v201 row_ror:1 row_mask:0xf bank_mask:0xf
	v_add_f32_dpp v202, v202, v202 row_ror:1 row_mask:0xf bank_mask:0xf
	v_add_f32_dpp v203, v203, v203 row_ror:1 row_mask:0xf bank_mask:0xf
	v_add_f32_dpp v204, v204, v204 row_ror:1 row_mask:0xf bank_mask:0xf
	v_add_f32_dpp v205, v205, v205 row_ror:1 row_mask:0xf bank_mask:0xf
	v_add_f32_dpp v206, v206, v206 row_ror:1 row_mask:0xf bank_mask:0xf
	v_add_f32_dpp v207, v207, v207 row_ror:1 row_mask:0xf bank_mask:0xf
	v_add_f32_dpp v208, v208, v208 row_ror:1 row_mask:0xf bank_mask:0xf
	v_add_f32_dpp v209, v209, v209 row_ror:1 row_mask:0xf bank_mask:0xf
	v_add_f32_dpp v210, v210, v210 row_ror:1 row_mask:0xf bank_mask:0xf
	v_add_f32_dpp v211, v211, v211 row_ror:1 row_mask:0xf bank_mask:0xf
	v_add_f32_dpp v212, v212, v212 row_ror:1 row_mask:0xf bank_mask:0xf
	v_add_f32_dpp v213, v213, v213 row_ror:1 row_mask:0xf bank_mask:0xf
	v_add_f32_dpp v214, v214, v214 row_ror:1 row_mask:0xf bank_mask:0xf
	v_add_f32_dpp v215, v215, v215 row_ror:1 row_mask:0xf bank_mask:0xf
	v_add_f32_dpp v216, v216, v216 row_ror:1 row_mask:0xf bank_mask:0xf
	v_add_f32_dpp v217, v217, v217 row_ror:1 row_mask:0xf bank_mask:0xf
	v_add_f32_dpp v218, v218, v218 row_ror:1 row_mask:0xf bank_mask:0xf
	v_add_f32_dpp v219, v219, v219 row_ror:1 row_mask:0xf bank_mask:0xf
	v_add_f32_dpp v220, v220, v220 row_ror:1 row_mask:0xf bank_mask:0xf
	v_add_f32_dpp v221, v221, v221 row_ror:1 row_mask:0xf bank_mask:0xf
	v_add_f32_dpp v222, v222, v222 row_ror:1 row_mask:0xf bank_mask:0xf
	v_add_f32_dpp v223, v223, v223 row_ror:1 row_mask:0xf bank_mask:0xf
	v_add_f32_dpp v224, v224, v224 row_ror:1 row_mask:0xf bank_mask:0xf
	v_add_f32_dpp v225, v225, v225 row_ror:1 row_mask:0xf bank_mask:0xf
	v_lshlrev_b32_e32 v236, 10, v162
	v_lshl_add_u32 v236, v163, 2, v236
	v_add_u32_e32 v236, 0x20000, v236
	v_cmp_eq_u32_e32 vcc, 0, v160
	s_and_saveexec_b64 s[0:1], vcc
	ds_write_b128 v236, v[194:197]
	ds_write_b128 v236, v[198:201] offset:64
	ds_write_b128 v236, v[202:205] offset:128
	ds_write_b128 v236, v[206:209] offset:192
	ds_write_b128 v236, v[210:213] offset:512
	ds_write_b128 v236, v[214:217] offset:576
	ds_write_b128 v236, v[218:221] offset:640
	ds_write_b128 v236, v[222:225] offset:704
	s_or_b64 exec, exec, s[0:1]
	v_readfirstlane_b32 s32, v167
	s_waitcnt lgkmcnt(0)
	s_barrier
	s_cmp_lt_u32 s32, 0x100
	s_cbranch_scc0 .Lgo_fz_w1
	v_lshlrev_b32_e32 v238, 2, v167
	v_add_u32_e32 v239, 0x20000, v238
	ds_read_b32 v240, v239
	ds_read_b32 v241, v239 offset:1024
	ds_read_b32 v242, v239 offset:2048
	ds_read_b32 v243, v239 offset:3072
	s_lshr_b32 s0, s36, 8
	s_lshl_b32 s1, s0, 3
	s_lshr_b32 s2, s34, 8
	s_add_u32 s1, s1, s2
	s_lshl_b32 s1, s1, 10
	v_add_u32_e32 v244, s1, v238
	s_waitcnt lgkmcnt(0)
	v_add_f32_e32 v240, v240, v241
	v_add_f32_e32 v240, v240, v242
	v_add_f32_e32 v240, v240, v243
	global_store_dword v244, v240, s[94:95] sc0 sc1
	s_waitcnt vmcnt(0)
.Lgo_fz_w1:
	s_barrier
	s_cmp_lt_u32 s32, 64
	s_cbranch_scc0 .Lgo_fz_w2
	s_lshr_b32 s0, s36, 8
	s_lshl_b32 s0, s0, 2
	s_add_u32 s0, s0, 0x204
	v_mov_b32_e32 v245, s0
	v_mov_b32_e32 v246, 1
	s_mov_b64 exec, 1
	global_atomic_add v245, v246, s[98:99]
	s_mov_b32 s2, 0
.Lgo_fz_poll:
	global_load_dword v247, v245, s[98:99] sc1
	s_waitcnt vmcnt(0)
	v_readfirstlane_b32 s1, v247
	s_cmp_ge_u32 s1, 8
	s_cbranch_scc1 .Lgo_fz_got
	s_sleep 1
	s_add_u32 s2, s2, 1
	s_cmp_lt_u32 s2, 0x200000
	s_cbranch_scc1 .Lgo_fz_poll
.Lgo_fz_got:
	s_mov_b64 exec, -1
	buffer_inv sc1
	s_waitcnt vmcnt(0)
.Lgo_fz_w2:
	s_barrier
	s_cmp_lt_u32 s32, 0x100
	s_cbranch_scc0 .Lgo_fz_w3
	s_lshr_b32 s0, s36, 8
	s_lshl_b32 s0, s0, 13
	v_add_u32_e32 v244, s0, v238
	v_add_u32_e32 v245, 0x1000, v244
	global_load_dword v246, v244, s[94:95] sc0 sc1
	global_load_dword v247, v244, s[94:95] offset:1024 sc0 sc1
	global_load_dword v248, v244, s[94:95] offset:2048 sc0 sc1
	global_load_dword v249, v244, s[94:95] offset:3072 sc0 sc1
	global_load_dword v250, v245, s[94:95] sc0 sc1
	global_load_dword v251, v245, s[94:95] offset:1024 sc0 sc1
	global_load_dword v252, v245, s[94:95] offset:2048 sc0 sc1
	global_load_dword v253, v245, s[94:95] offset:3072 sc0 sc1
	s_waitcnt vmcnt(0)
	v_add_f32_e32 v246, v246, v247
	v_add_f32_e32 v246, v246, v248
	v_add_f32_e32 v246, v246, v249
	v_add_f32_e32 v246, v246, v250
	v_add_f32_e32 v246, v246, v251
	v_add_f32_e32 v246, v246, v252
	v_add_f32_e32 v246, v246, v253
	v_fmamk_f32 v246, v246, 0x3a000000, v166
	v_mul_f32_e32 v247, 0x4b800000, v246
	v_cmp_gt_f32_e32 vcc, s58, v246
	s_nop 1
	v_cndmask_b32_e32 v246, v246, v247, vcc
	v_rsq_f32_e32 v248, v246
	s_nop 0
	v_mul_f32_e32 v247, 0x45800000, v248
	v_cndmask_b32_e32 v248, v248, v247, vcc
	ds_write_b32 v239, v248
	s_waitcnt lgkmcnt(0)
.Lgo_fz_w3:
	s_barrier
	v_lshlrev_b32_e32 v236, 2, v163
	v_add_u32_e32 v236, 0x20000, v236
	ds_read_b128 v[194:197], v236
	ds_read_b128 v[198:201], v236 offset:64
	ds_read_b128 v[202:205], v236 offset:128
	ds_read_b128 v[206:209], v236 offset:192
	ds_read_b128 v[210:213], v236 offset:512
	ds_read_b128 v[214:217], v236 offset:576
	ds_read_b128 v[218:221], v236 offset:640
	ds_read_b128 v[222:225], v236 offset:704
	s_load_dwordx2 s[94:95], s[88:89], 0xc8
	s_load_dwordx2 s[98:99], s[88:89], 0xf0
	s_load_dwordx2 s[2:3], s[88:89], 0xc0
	v_lshlrev_b32_e32 v237, 2, v164
	s_lshl_b32 s0, s34, 2
	v_add_u32_e32 v237, s0, v237
	v_add_u32_e32 v168, s36, v163
	v_lshlrev_b32_e32 v168, 13, v168
	v_add_u32_e32 v168, v168, v237
	v_add_u32_e32 v169, 0x2000, v168
	v_add_u32_e32 v170, 0x4000, v168
	v_add_u32_e32 v171, 0x6000, v168
	s_lshr_b32 s0, s36, 12
	s_add_u32 s0, s0, 5
	s_mul_i32 s0, s0, 0x6000
	s_add_u32 s0, s0, 0x4000
	s_waitcnt lgkmcnt(0)
	s_add_u32 s98, s98, s0
	s_addc_u32 s99, s99, 0
	s_add_u32 s2, s2, 0x2000
	s_addc_u32 s3, s3, 0
	global_load_dword v226, v237, s[98:99]
	global_load_dword v230, v237, s[2:3]
	global_load_dword v227, v237, s[98:99] offset:64
	global_load_dword v231, v237, s[2:3] offset:64
	global_load_dword v228, v237, s[98:99] offset:512
	global_load_dword v232, v237, s[2:3] offset:512
	global_load_dword v229, v237, s[98:99] offset:576
	global_load_dword v233, v237, s[2:3] offset:576
	v_mov_b32_e32 v172, v168
	v_mov_b32_e32 v173, v169
	v_mov_b32_e32 v174, v170
	v_mov_b32_e32 v175, v171
	global_load_dword v128, v172, s[94:95]
	global_load_dword v129, v173, s[94:95]
	global_load_dword v130, v174, s[94:95]
	global_load_dword v131, v175, s[94:95]
	global_load_dword v132, v172, s[94:95] offset:64
	global_load_dword v133, v173, s[94:95] offset:64
	global_load_dword v134, v174, s[94:95] offset:64
	global_load_dword v135, v175, s[94:95] offset:64
	global_load_dword v136, v172, s[94:95] offset:512
	global_load_dword v137, v173, s[94:95] offset:512
	global_load_dword v138, v174, s[94:95] offset:512
	global_load_dword v139, v175, s[94:95] offset:512
	global_load_dword v140, v172, s[94:95] offset:576
	global_load_dword v141, v173, s[94:95] offset:576
	global_load_dword v142, v174, s[94:95] offset:576
	global_load_dword v143, v175, s[94:95] offset:576
	v_add_u32_e32 v176, 0x20000, v168
	v_add_u32_e32 v177, 0x20000, v169
	v_add_u32_e32 v178, 0x20000, v170
	v_add_u32_e32 v179, 0x20000, v171
	global_load_dword v144, v176, s[94:95]
	global_load_dword v145, v177, s[94:95]
	global_load_dword v146, v178, s[94:95]
	global_load_dword v147, v179, s[94:95]
	global_load_dword v148, v176, s[94:95] offset:64
	global_load_dword v149, v177, s[94:95] offset:64
	global_load_dword v150, v178, s[94:95] offset:64
	global_load_dword v151, v179, s[94:95] offset:64
	global_load_dword v152, v176, s[94:95] offset:512
	global_load_dword v153, v177, s[94:95] offset:512
	global_load_dword v154, v178, s[94:95] offset:512
	global_load_dword v155, v179, s[94:95] offset:512
	global_load_dword v156, v176, s[94:95] offset:576
	global_load_dword v157, v177, s[94:95] offset:576
	global_load_dword v158, v178, s[94:95] offset:576
	global_load_dword v159, v179, s[94:95] offset:576
	s_waitcnt vmcnt(16)
	v_mul_f32_e32 v124, v124, v226
	v_mul_f32_e32 v124, v124, v194
	v_fma_f32 v124, v124, v230, v128
	v_mul_f32_e32 v125, v125, v226
	v_mul_f32_e32 v125, v125, v195
	v_fma_f32 v125, v125, v230, v129
	v_mul_f32_e32 v126, v126, v226
	v_mul_f32_e32 v126, v126, v196
	v_fma_f32 v126, v126, v230, v130
	v_mul_f32_e32 v127, v127, v226
	v_mul_f32_e32 v127, v127, v197
	v_fma_f32 v127, v127, v230, v131
	v_mul_f32_e32 v120, v120, v227
	v_mul_f32_e32 v120, v120, v194
	v_fma_f32 v120, v120, v231, v132
	v_mul_f32_e32 v121, v121, v227
	v_mul_f32_e32 v121, v121, v195
	v_fma_f32 v121, v121, v231, v133
	v_mul_f32_e32 v122, v122, v227
	v_mul_f32_e32 v122, v122, v196
	v_fma_f32 v122, v122, v231, v134
	v_mul_f32_e32 v123, v123, v227
	v_mul_f32_e32 v123, v123, v197
	v_fma_f32 v123, v123, v231, v135
	v_mul_f32_e32 v100, v100, v228
	v_mul_f32_e32 v100, v100, v194
	v_fma_f32 v100, v100, v232, v136
	v_mul_f32_e32 v101, v101, v228
	v_mul_f32_e32 v101, v101, v195
	v_fma_f32 v101, v101, v232, v137
	v_mul_f32_e32 v102, v102, v228
	v_mul_f32_e32 v102, v102, v196
	v_fma_f32 v102, v102, v232, v138
	v_mul_f32_e32 v103, v103, v228
	v_mul_f32_e32 v103, v103, v197
	v_fma_f32 v103, v103, v232, v139
	v_mul_f32_e32 v96, v96, v229
	v_mul_f32_e32 v96, v96, v194
	v_fma_f32 v96, v96, v233, v140
	v_mul_f32_e32 v97, v97, v229
	v_mul_f32_e32 v97, v97, v195
	v_fma_f32 v97, v97, v233, v141
	v_mul_f32_e32 v98, v98, v229
	v_mul_f32_e32 v98, v98, v196
	v_fma_f32 v98, v98, v233, v142
	v_mul_f32_e32 v99, v99, v229
	v_mul_f32_e32 v99, v99, v197
	v_fma_f32 v99, v99, v233, v143
	global_store_dword v172, v124, s[94:95]
	global_store_dword v173, v125, s[94:95]
	global_store_dword v174, v126, s[94:95]
	global_store_dword v175, v127, s[94:95]
	global_store_dword v172, v120, s[94:95] offset:64
	global_store_dword v173, v121, s[94:95] offset:64
	global_store_dword v174, v122, s[94:95] offset:64
	global_store_dword v175, v123, s[94:95] offset:64
	global_store_dword v172, v100, s[94:95] offset:512
	global_store_dword v173, v101, s[94:95] offset:512
	global_store_dword v174, v102, s[94:95] offset:512
	global_store_dword v175, v103, s[94:95] offset:512
	global_store_dword v172, v96, s[94:95] offset:576
	global_store_dword v173, v97, s[94:95] offset:576
	global_store_dword v174, v98, s[94:95] offset:576
	global_store_dword v175, v99, s[94:95] offset:576
	v_add_u32_e32 v172, 0x40000, v168
	v_add_u32_e32 v173, 0x40000, v169
	v_add_u32_e32 v174, 0x40000, v170
	v_add_u32_e32 v175, 0x40000, v171
	global_load_dword v128, v172, s[94:95]
	global_load_dword v129, v173, s[94:95]
	global_load_dword v130, v174, s[94:95]
	global_load_dword v131, v175, s[94:95]
	global_load_dword v132, v172, s[94:95] offset:64
	global_load_dword v133, v173, s[94:95] offset:64
	global_load_dword v134, v174, s[94:95] offset:64
	global_load_dword v135, v175, s[94:95] offset:64
	global_load_dword v136, v172, s[94:95] offset:512
	global_load_dword v137, v173, s[94:95] offset:512
	global_load_dword v138, v174, s[94:95] offset:512
	global_load_dword v139, v175, s[94:95] offset:512
	global_load_dword v140, v172, s[94:95] offset:576
	global_load_dword v141, v173, s[94:95] offset:576
	global_load_dword v142, v174, s[94:95] offset:576
	global_load_dword v143, v175, s[94:95] offset:576
	s_waitcnt vmcnt(32)
	v_mul_f32_e32 v116, v116, v226
	v_mul_f32_e32 v116, v116, v198
	v_fma_f32 v116, v116, v230, v144
	v_mul_f32_e32 v117, v117, v226
	v_mul_f32_e32 v117, v117, v199
	v_fma_f32 v117, v117, v230, v145
	v_mul_f32_e32 v118, v118, v226
	v_mul_f32_e32 v118, v118, v200
	v_fma_f32 v118, v118, v230, v146
	v_mul_f32_e32 v119, v119, v226
	v_mul_f32_e32 v119, v119, v201
	v_fma_f32 v119, v119, v230, v147
	v_mul_f32_e32 v112, v112, v227
	v_mul_f32_e32 v112, v112, v198
	v_fma_f32 v112, v112, v231, v148
	v_mul_f32_e32 v113, v113, v227
	v_mul_f32_e32 v113, v113, v199
	v_fma_f32 v113, v113, v231, v149
	v_mul_f32_e32 v114, v114, v227
	v_mul_f32_e32 v114, v114, v200
	v_fma_f32 v114, v114, v231, v150
	v_mul_f32_e32 v115, v115, v227
	v_mul_f32_e32 v115, v115, v201
	v_fma_f32 v115, v115, v231, v151
	v_mul_f32_e32 v92, v92, v228
	v_mul_f32_e32 v92, v92, v198
	v_fma_f32 v92, v92, v232, v152
	v_mul_f32_e32 v93, v93, v228
	v_mul_f32_e32 v93, v93, v199
	v_fma_f32 v93, v93, v232, v153
	v_mul_f32_e32 v94, v94, v228
	v_mul_f32_e32 v94, v94, v200
	v_fma_f32 v94, v94, v232, v154
	v_mul_f32_e32 v95, v95, v228
	v_mul_f32_e32 v95, v95, v201
	v_fma_f32 v95, v95, v232, v155
	v_mul_f32_e32 v88, v88, v229
	v_mul_f32_e32 v88, v88, v198
	v_fma_f32 v88, v88, v233, v156
	v_mul_f32_e32 v89, v89, v229
	v_mul_f32_e32 v89, v89, v199
	v_fma_f32 v89, v89, v233, v157
	v_mul_f32_e32 v90, v90, v229
	v_mul_f32_e32 v90, v90, v200
	v_fma_f32 v90, v90, v233, v158
	v_mul_f32_e32 v91, v91, v229
	v_mul_f32_e32 v91, v91, v201
	v_fma_f32 v91, v91, v233, v159
	global_store_dword v176, v116, s[94:95]
	global_store_dword v177, v117, s[94:95]
	global_store_dword v178, v118, s[94:95]
	global_store_dword v179, v119, s[94:95]
	global_store_dword v176, v112, s[94:95] offset:64
	global_store_dword v177, v113, s[94:95] offset:64
	global_store_dword v178, v114, s[94:95] offset:64
	global_store_dword v179, v115, s[94:95] offset:64
	global_store_dword v176, v92, s[94:95] offset:512
	global_store_dword v177, v93, s[94:95] offset:512
	global_store_dword v178, v94, s[94:95] offset:512
	global_store_dword v179, v95, s[94:95] offset:512
	global_store_dword v176, v88, s[94:95] offset:576
	global_store_dword v177, v89, s[94:95] offset:576
	global_store_dword v178, v90, s[94:95] offset:576
	global_store_dword v179, v91, s[94:95] offset:576
	v_add_u32_e32 v176, 0x60000, v168
	v_add_u32_e32 v177, 0x60000, v169
	v_add_u32_e32 v178, 0x60000, v170
	v_add_u32_e32 v179, 0x60000, v171
	global_load_dword v144, v176, s[94:95]
	global_load_dword v145, v177, s[94:95]
	global_load_dword v146, v178, s[94:95]
	global_load_dword v147, v179, s[94:95]
	global_load_dword v148, v176, s[94:95] offset:64
	global_load_dword v149, v177, s[94:95] offset:64
	global_load_dword v150, v178, s[94:95] offset:64
	global_load_dword v151, v179, s[94:95] offset:64
	global_load_dword v152, v176, s[94:95] offset:512
	global_load_dword v153, v177, s[94:95] offset:512
	global_load_dword v154, v178, s[94:95] offset:512
	global_load_dword v155, v179, s[94:95] offset:512
	global_load_dword v156, v176, s[94:95] offset:576
	global_load_dword v157, v177, s[94:95] offset:576
	global_load_dword v158, v178, s[94:95] offset:576
	global_load_dword v159, v179, s[94:95] offset:576
	s_waitcnt vmcnt(32)
	v_mul_f32_e32 v108, v108, v226
	v_mul_f32_e32 v108, v108, v202
	v_fma_f32 v108, v108, v230, v128
	v_mul_f32_e32 v109, v109, v226
	v_mul_f32_e32 v109, v109, v203
	v_fma_f32 v109, v109, v230, v129
	v_mul_f32_e32 v110, v110, v226
	v_mul_f32_e32 v110, v110, v204
	v_fma_f32 v110, v110, v230, v130
	v_mul_f32_e32 v111, v111, v226
	v_mul_f32_e32 v111, v111, v205
	v_fma_f32 v111, v111, v230, v131
	v_mul_f32_e32 v104, v104, v227
	v_mul_f32_e32 v104, v104, v202
	v_fma_f32 v104, v104, v231, v132
	v_mul_f32_e32 v105, v105, v227
	v_mul_f32_e32 v105, v105, v203
	v_fma_f32 v105, v105, v231, v133
	v_mul_f32_e32 v106, v106, v227
	v_mul_f32_e32 v106, v106, v204
	v_fma_f32 v106, v106, v231, v134
	v_mul_f32_e32 v107, v107, v227
	v_mul_f32_e32 v107, v107, v205
	v_fma_f32 v107, v107, v231, v135
	v_mul_f32_e32 v80, v80, v228
	v_mul_f32_e32 v80, v80, v202
	v_fma_f32 v80, v80, v232, v136
	v_mul_f32_e32 v81, v81, v228
	v_mul_f32_e32 v81, v81, v203
	v_fma_f32 v81, v81, v232, v137
	v_mul_f32_e32 v82, v82, v228
	v_mul_f32_e32 v82, v82, v204
	v_fma_f32 v82, v82, v232, v138
	v_mul_f32_e32 v83, v83, v228
	v_mul_f32_e32 v83, v83, v205
	v_fma_f32 v83, v83, v232, v139
	v_mul_f32_e32 v72, v72, v229
	v_mul_f32_e32 v72, v72, v202
	v_fma_f32 v72, v72, v233, v140
	v_mul_f32_e32 v73, v73, v229
	v_mul_f32_e32 v73, v73, v203
	v_fma_f32 v73, v73, v233, v141
	v_mul_f32_e32 v74, v74, v229
	v_mul_f32_e32 v74, v74, v204
	v_fma_f32 v74, v74, v233, v142
	v_mul_f32_e32 v75, v75, v229
	v_mul_f32_e32 v75, v75, v205
	v_fma_f32 v75, v75, v233, v143
	global_store_dword v172, v108, s[94:95]
	global_store_dword v173, v109, s[94:95]
	global_store_dword v174, v110, s[94:95]
	global_store_dword v175, v111, s[94:95]
	global_store_dword v172, v104, s[94:95] offset:64
	global_store_dword v173, v105, s[94:95] offset:64
	global_store_dword v174, v106, s[94:95] offset:64
	global_store_dword v175, v107, s[94:95] offset:64
	global_store_dword v172, v80, s[94:95] offset:512
	global_store_dword v173, v81, s[94:95] offset:512
	global_store_dword v174, v82, s[94:95] offset:512
	global_store_dword v175, v83, s[94:95] offset:512
	global_store_dword v172, v72, s[94:95] offset:576
	global_store_dword v173, v73, s[94:95] offset:576
	global_store_dword v174, v74, s[94:95] offset:576
	global_store_dword v175, v75, s[94:95] offset:576
	v_add_u32_e32 v172, 0x100000, v168
	v_add_u32_e32 v173, 0x100000, v169
	v_add_u32_e32 v174, 0x100000, v170
	v_add_u32_e32 v175, 0x100000, v171
	global_load_dword v128, v172, s[94:95]
	global_load_dword v129, v173, s[94:95]
	global_load_dword v130, v174, s[94:95]
	global_load_dword v131, v175, s[94:95]
	global_load_dword v132, v172, s[94:95] offset:64
	global_load_dword v133, v173, s[94:95] offset:64
	global_load_dword v134, v174, s[94:95] offset:64
	global_load_dword v135, v175, s[94:95] offset:64
	global_load_dword v136, v172, s[94:95] offset:512
	global_load_dword v137, v173, s[94:95] offset:512
	global_load_dword v138, v174, s[94:95] offset:512
	global_load_dword v139, v175, s[94:95] offset:512
	global_load_dword v140, v172, s[94:95] offset:576
	global_load_dword v141, v173, s[94:95] offset:576
	global_load_dword v142, v174, s[94:95] offset:576
	global_load_dword v143, v175, s[94:95] offset:576
	s_waitcnt vmcnt(32)
	v_mul_f32_e32 v84, v84, v226
	v_mul_f32_e32 v84, v84, v206
	v_fma_f32 v84, v84, v230, v144
	v_mul_f32_e32 v85, v85, v226
	v_mul_f32_e32 v85, v85, v207
	v_fma_f32 v85, v85, v230, v145
	v_mul_f32_e32 v86, v86, v226
	v_mul_f32_e32 v86, v86, v208
	v_fma_f32 v86, v86, v230, v146
	v_mul_f32_e32 v87, v87, v226
	v_mul_f32_e32 v87, v87, v209
	v_fma_f32 v87, v87, v230, v147
	v_mul_f32_e32 v76, v76, v227
	v_mul_f32_e32 v76, v76, v206
	v_fma_f32 v76, v76, v231, v148
	v_mul_f32_e32 v77, v77, v227
	v_mul_f32_e32 v77, v77, v207
	v_fma_f32 v77, v77, v231, v149
	v_mul_f32_e32 v78, v78, v227
	v_mul_f32_e32 v78, v78, v208
	v_fma_f32 v78, v78, v231, v150
	v_mul_f32_e32 v79, v79, v227
	v_mul_f32_e32 v79, v79, v209
	v_fma_f32 v79, v79, v231, v151
	v_mul_f32_e32 v68, v68, v228
	v_mul_f32_e32 v68, v68, v206
	v_fma_f32 v68, v68, v232, v152
	v_mul_f32_e32 v69, v69, v228
	v_mul_f32_e32 v69, v69, v207
	v_fma_f32 v69, v69, v232, v153
	v_mul_f32_e32 v70, v70, v228
	v_mul_f32_e32 v70, v70, v208
	v_fma_f32 v70, v70, v232, v154
	v_mul_f32_e32 v71, v71, v228
	v_mul_f32_e32 v71, v71, v209
	v_fma_f32 v71, v71, v232, v155
	v_mul_f32_e32 v64, v64, v229
	v_mul_f32_e32 v64, v64, v206
	v_fma_f32 v64, v64, v233, v156
	v_mul_f32_e32 v65, v65, v229
	v_mul_f32_e32 v65, v65, v207
	v_fma_f32 v65, v65, v233, v157
	v_mul_f32_e32 v66, v66, v229
	v_mul_f32_e32 v66, v66, v208
	v_fma_f32 v66, v66, v233, v158
	v_mul_f32_e32 v67, v67, v229
	v_mul_f32_e32 v67, v67, v209
	v_fma_f32 v67, v67, v233, v159
	global_store_dword v176, v84, s[94:95]
	global_store_dword v177, v85, s[94:95]
	global_store_dword v178, v86, s[94:95]
	global_store_dword v179, v87, s[94:95]
	global_store_dword v176, v76, s[94:95] offset:64
	global_store_dword v177, v77, s[94:95] offset:64
	global_store_dword v178, v78, s[94:95] offset:64
	global_store_dword v179, v79, s[94:95] offset:64
	global_store_dword v176, v68, s[94:95] offset:512
	global_store_dword v177, v69, s[94:95] offset:512
	global_store_dword v178, v70, s[94:95] offset:512
	global_store_dword v179, v71, s[94:95] offset:512
	global_store_dword v176, v64, s[94:95] offset:576
	global_store_dword v177, v65, s[94:95] offset:576
	global_store_dword v178, v66, s[94:95] offset:576
	global_store_dword v179, v67, s[94:95] offset:576
	v_add_u32_e32 v176, 0x120000, v168
	v_add_u32_e32 v177, 0x120000, v169
	v_add_u32_e32 v178, 0x120000, v170
	v_add_u32_e32 v179, 0x120000, v171
	global_load_dword v144, v176, s[94:95]
	global_load_dword v145, v177, s[94:95]
	global_load_dword v146, v178, s[94:95]
	global_load_dword v147, v179, s[94:95]
	global_load_dword v148, v176, s[94:95] offset:64
	global_load_dword v149, v177, s[94:95] offset:64
	global_load_dword v150, v178, s[94:95] offset:64
	global_load_dword v151, v179, s[94:95] offset:64
	global_load_dword v152, v176, s[94:95] offset:512
	global_load_dword v153, v177, s[94:95] offset:512
	global_load_dword v154, v178, s[94:95] offset:512
	global_load_dword v155, v179, s[94:95] offset:512
	global_load_dword v156, v176, s[94:95] offset:576
	global_load_dword v157, v177, s[94:95] offset:576
	global_load_dword v158, v178, s[94:95] offset:576
	global_load_dword v159, v179, s[94:95] offset:576
	s_waitcnt vmcnt(32)
	v_mul_f32_e32 v60, v60, v226
	v_mul_f32_e32 v60, v60, v210
	v_fma_f32 v60, v60, v230, v128
	v_mul_f32_e32 v61, v61, v226
	v_mul_f32_e32 v61, v61, v211
	v_fma_f32 v61, v61, v230, v129
	v_mul_f32_e32 v62, v62, v226
	v_mul_f32_e32 v62, v62, v212
	v_fma_f32 v62, v62, v230, v130
	v_mul_f32_e32 v63, v63, v226
	v_mul_f32_e32 v63, v63, v213
	v_fma_f32 v63, v63, v230, v131
	v_mul_f32_e32 v56, v56, v227
	v_mul_f32_e32 v56, v56, v210
	v_fma_f32 v56, v56, v231, v132
	v_mul_f32_e32 v57, v57, v227
	v_mul_f32_e32 v57, v57, v211
	v_fma_f32 v57, v57, v231, v133
	v_mul_f32_e32 v58, v58, v227
	v_mul_f32_e32 v58, v58, v212
	v_fma_f32 v58, v58, v231, v134
	v_mul_f32_e32 v59, v59, v227
	v_mul_f32_e32 v59, v59, v213
	v_fma_f32 v59, v59, v231, v135
	v_mul_f32_e32 v32, v32, v228
	v_mul_f32_e32 v32, v32, v210
	v_fma_f32 v32, v32, v232, v136
	v_mul_f32_e32 v33, v33, v228
	v_mul_f32_e32 v33, v33, v211
	v_fma_f32 v33, v33, v232, v137
	v_mul_f32_e32 v34, v34, v228
	v_mul_f32_e32 v34, v34, v212
	v_fma_f32 v34, v34, v232, v138
	v_mul_f32_e32 v35, v35, v228
	v_mul_f32_e32 v35, v35, v213
	v_fma_f32 v35, v35, v232, v139
	v_mul_f32_e32 v24, v24, v229
	v_mul_f32_e32 v24, v24, v210
	v_fma_f32 v24, v24, v233, v140
	v_mul_f32_e32 v25, v25, v229
	v_mul_f32_e32 v25, v25, v211
	v_fma_f32 v25, v25, v233, v141
	v_mul_f32_e32 v26, v26, v229
	v_mul_f32_e32 v26, v26, v212
	v_fma_f32 v26, v26, v233, v142
	v_mul_f32_e32 v27, v27, v229
	v_mul_f32_e32 v27, v27, v213
	v_fma_f32 v27, v27, v233, v143
	global_store_dword v172, v60, s[94:95]
	global_store_dword v173, v61, s[94:95]
	global_store_dword v174, v62, s[94:95]
	global_store_dword v175, v63, s[94:95]
	global_store_dword v172, v56, s[94:95] offset:64
	global_store_dword v173, v57, s[94:95] offset:64
	global_store_dword v174, v58, s[94:95] offset:64
	global_store_dword v175, v59, s[94:95] offset:64
	global_store_dword v172, v32, s[94:95] offset:512
	global_store_dword v173, v33, s[94:95] offset:512
	global_store_dword v174, v34, s[94:95] offset:512
	global_store_dword v175, v35, s[94:95] offset:512
	global_store_dword v172, v24, s[94:95] offset:576
	global_store_dword v173, v25, s[94:95] offset:576
	global_store_dword v174, v26, s[94:95] offset:576
	global_store_dword v175, v27, s[94:95] offset:576
	v_add_u32_e32 v172, 0x140000, v168
	v_add_u32_e32 v173, 0x140000, v169
	v_add_u32_e32 v174, 0x140000, v170
	v_add_u32_e32 v175, 0x140000, v171
	global_load_dword v128, v172, s[94:95]
	global_load_dword v129, v173, s[94:95]
	global_load_dword v130, v174, s[94:95]
	global_load_dword v131, v175, s[94:95]
	global_load_dword v132, v172, s[94:95] offset:64
	global_load_dword v133, v173, s[94:95] offset:64
	global_load_dword v134, v174, s[94:95] offset:64
	global_load_dword v135, v175, s[94:95] offset:64
	global_load_dword v136, v172, s[94:95] offset:512
	global_load_dword v137, v173, s[94:95] offset:512
	global_load_dword v138, v174, s[94:95] offset:512
	global_load_dword v139, v175, s[94:95] offset:512
	global_load_dword v140, v172, s[94:95] offset:576
	global_load_dword v141, v173, s[94:95] offset:576
	global_load_dword v142, v174, s[94:95] offset:576
	global_load_dword v143, v175, s[94:95] offset:576
	s_waitcnt vmcnt(32)
	v_mul_f32_e32 v52, v52, v226
	v_mul_f32_e32 v52, v52, v214
	v_fma_f32 v52, v52, v230, v144
	v_mul_f32_e32 v53, v53, v226
	v_mul_f32_e32 v53, v53, v215
	v_fma_f32 v53, v53, v230, v145
	v_mul_f32_e32 v54, v54, v226
	v_mul_f32_e32 v54, v54, v216
	v_fma_f32 v54, v54, v230, v146
	v_mul_f32_e32 v55, v55, v226
	v_mul_f32_e32 v55, v55, v217
	v_fma_f32 v55, v55, v230, v147
	v_mul_f32_e32 v48, v48, v227
	v_mul_f32_e32 v48, v48, v214
	v_fma_f32 v48, v48, v231, v148
	v_mul_f32_e32 v49, v49, v227
	v_mul_f32_e32 v49, v49, v215
	v_fma_f32 v49, v49, v231, v149
	v_mul_f32_e32 v50, v50, v227
	v_mul_f32_e32 v50, v50, v216
	v_fma_f32 v50, v50, v231, v150
	v_mul_f32_e32 v51, v51, v227
	v_mul_f32_e32 v51, v51, v217
	v_fma_f32 v51, v51, v231, v151
	v_mul_f32_e32 v20, v20, v228
	v_mul_f32_e32 v20, v20, v214
	v_fma_f32 v20, v20, v232, v152
	v_mul_f32_e32 v21, v21, v228
	v_mul_f32_e32 v21, v21, v215
	v_fma_f32 v21, v21, v232, v153
	v_mul_f32_e32 v22, v22, v228
	v_mul_f32_e32 v22, v22, v216
	v_fma_f32 v22, v22, v232, v154
	v_mul_f32_e32 v23, v23, v228
	v_mul_f32_e32 v23, v23, v217
	v_fma_f32 v23, v23, v232, v155
	v_mul_f32_e32 v16, v16, v229
	v_mul_f32_e32 v16, v16, v214
	v_fma_f32 v16, v16, v233, v156
	v_mul_f32_e32 v17, v17, v229
	v_mul_f32_e32 v17, v17, v215
	v_fma_f32 v17, v17, v233, v157
	v_mul_f32_e32 v18, v18, v229
	v_mul_f32_e32 v18, v18, v216
	v_fma_f32 v18, v18, v233, v158
	v_mul_f32_e32 v19, v19, v229
	v_mul_f32_e32 v19, v19, v217
	v_fma_f32 v19, v19, v233, v159
	global_store_dword v176, v52, s[94:95]
	global_store_dword v177, v53, s[94:95]
	global_store_dword v178, v54, s[94:95]
	global_store_dword v179, v55, s[94:95]
	global_store_dword v176, v48, s[94:95] offset:64
	global_store_dword v177, v49, s[94:95] offset:64
	global_store_dword v178, v50, s[94:95] offset:64
	global_store_dword v179, v51, s[94:95] offset:64
	global_store_dword v176, v20, s[94:95] offset:512
	global_store_dword v177, v21, s[94:95] offset:512
	global_store_dword v178, v22, s[94:95] offset:512
	global_store_dword v179, v23, s[94:95] offset:512
	global_store_dword v176, v16, s[94:95] offset:576
	global_store_dword v177, v17, s[94:95] offset:576
	global_store_dword v178, v18, s[94:95] offset:576
	global_store_dword v179, v19, s[94:95] offset:576
	v_add_u32_e32 v176, 0x160000, v168
	v_add_u32_e32 v177, 0x160000, v169
	v_add_u32_e32 v178, 0x160000, v170
	v_add_u32_e32 v179, 0x160000, v171
	global_load_dword v144, v176, s[94:95]
	global_load_dword v145, v177, s[94:95]
	global_load_dword v146, v178, s[94:95]
	global_load_dword v147, v179, s[94:95]
	global_load_dword v148, v176, s[94:95] offset:64
	global_load_dword v149, v177, s[94:95] offset:64
	global_load_dword v150, v178, s[94:95] offset:64
	global_load_dword v151, v179, s[94:95] offset:64
	global_load_dword v152, v176, s[94:95] offset:512
	global_load_dword v153, v177, s[94:95] offset:512
	global_load_dword v154, v178, s[94:95] offset:512
	global_load_dword v155, v179, s[94:95] offset:512
	global_load_dword v156, v176, s[94:95] offset:576
	global_load_dword v157, v177, s[94:95] offset:576
	global_load_dword v158, v178, s[94:95] offset:576
	global_load_dword v159, v179, s[94:95] offset:576
	s_waitcnt vmcnt(32)
	v_mul_f32_e32 v44, v44, v226
	v_mul_f32_e32 v44, v44, v218
	v_fma_f32 v44, v44, v230, v128
	v_mul_f32_e32 v45, v45, v226
	v_mul_f32_e32 v45, v45, v219
	v_fma_f32 v45, v45, v230, v129
	v_mul_f32_e32 v46, v46, v226
	v_mul_f32_e32 v46, v46, v220
	v_fma_f32 v46, v46, v230, v130
	v_mul_f32_e32 v47, v47, v226
	v_mul_f32_e32 v47, v47, v221
	v_fma_f32 v47, v47, v230, v131
	v_mul_f32_e32 v40, v40, v227
	v_mul_f32_e32 v40, v40, v218
	v_fma_f32 v40, v40, v231, v132
	v_mul_f32_e32 v41, v41, v227
	v_mul_f32_e32 v41, v41, v219
	v_fma_f32 v41, v41, v231, v133
	v_mul_f32_e32 v42, v42, v227
	v_mul_f32_e32 v42, v42, v220
	v_fma_f32 v42, v42, v231, v134
	v_mul_f32_e32 v43, v43, v227
	v_mul_f32_e32 v43, v43, v221
	v_fma_f32 v43, v43, v231, v135
	v_mul_f32_e32 v12, v12, v228
	v_mul_f32_e32 v12, v12, v218
	v_fma_f32 v12, v12, v232, v136
	v_mul_f32_e32 v13, v13, v228
	v_mul_f32_e32 v13, v13, v219
	v_fma_f32 v13, v13, v232, v137
	v_mul_f32_e32 v14, v14, v228
	v_mul_f32_e32 v14, v14, v220
	v_fma_f32 v14, v14, v232, v138
	v_mul_f32_e32 v15, v15, v228
	v_mul_f32_e32 v15, v15, v221
	v_fma_f32 v15, v15, v232, v139
	v_mul_f32_e32 v8, v8, v229
	v_mul_f32_e32 v8, v8, v218
	v_fma_f32 v8, v8, v233, v140
	v_mul_f32_e32 v9, v9, v229
	v_mul_f32_e32 v9, v9, v219
	v_fma_f32 v9, v9, v233, v141
	v_mul_f32_e32 v10, v10, v229
	v_mul_f32_e32 v10, v10, v220
	v_fma_f32 v10, v10, v233, v142
	v_mul_f32_e32 v11, v11, v229
	v_mul_f32_e32 v11, v11, v221
	v_fma_f32 v11, v11, v233, v143
	global_store_dword v172, v44, s[94:95]
	global_store_dword v173, v45, s[94:95]
	global_store_dword v174, v46, s[94:95]
	global_store_dword v175, v47, s[94:95]
	global_store_dword v172, v40, s[94:95] offset:64
	global_store_dword v173, v41, s[94:95] offset:64
	global_store_dword v174, v42, s[94:95] offset:64
	global_store_dword v175, v43, s[94:95] offset:64
	global_store_dword v172, v12, s[94:95] offset:512
	global_store_dword v173, v13, s[94:95] offset:512
	global_store_dword v174, v14, s[94:95] offset:512
	global_store_dword v175, v15, s[94:95] offset:512
	global_store_dword v172, v8, s[94:95] offset:576
	global_store_dword v173, v9, s[94:95] offset:576
	global_store_dword v174, v10, s[94:95] offset:576
	global_store_dword v175, v11, s[94:95] offset:576
	s_waitcnt vmcnt(16)
	v_mul_f32_e32 v36, v36, v226
	v_mul_f32_e32 v36, v36, v222
	v_fma_f32 v36, v36, v230, v144
	v_mul_f32_e32 v37, v37, v226
	v_mul_f32_e32 v37, v37, v223
	v_fma_f32 v37, v37, v230, v145
	v_mul_f32_e32 v38, v38, v226
	v_mul_f32_e32 v38, v38, v224
	v_fma_f32 v38, v38, v230, v146
	v_mul_f32_e32 v39, v39, v226
	v_mul_f32_e32 v39, v39, v225
	v_fma_f32 v39, v39, v230, v147
	v_mul_f32_e32 v28, v28, v227
	v_mul_f32_e32 v28, v28, v222
	v_fma_f32 v28, v28, v231, v148
	v_mul_f32_e32 v29, v29, v227
	v_mul_f32_e32 v29, v29, v223
	v_fma_f32 v29, v29, v231, v149
	v_mul_f32_e32 v30, v30, v227
	v_mul_f32_e32 v30, v30, v224
	v_fma_f32 v30, v30, v231, v150
	v_mul_f32_e32 v31, v31, v227
	v_mul_f32_e32 v31, v31, v225
	v_fma_f32 v31, v31, v231, v151
	v_mul_f32_e32 v4, v4, v228
	v_mul_f32_e32 v4, v4, v222
	v_fma_f32 v4, v4, v232, v152
	v_mul_f32_e32 v5, v5, v228
	v_mul_f32_e32 v5, v5, v223
	v_fma_f32 v5, v5, v232, v153
	v_mul_f32_e32 v6, v6, v228
	v_mul_f32_e32 v6, v6, v224
	v_fma_f32 v6, v6, v232, v154
	v_mul_f32_e32 v7, v7, v228
	v_mul_f32_e32 v7, v7, v225
	v_fma_f32 v7, v7, v232, v155
	v_mul_f32_e32 v0, v0, v229
	v_mul_f32_e32 v0, v0, v222
	v_fma_f32 v0, v0, v233, v156
	v_mul_f32_e32 v1, v1, v229
	v_mul_f32_e32 v1, v1, v223
	v_fma_f32 v1, v1, v233, v157
	v_mul_f32_e32 v2, v2, v229
	v_mul_f32_e32 v2, v2, v224
	v_fma_f32 v2, v2, v233, v158
	v_mul_f32_e32 v3, v3, v229
	v_mul_f32_e32 v3, v3, v225
	v_fma_f32 v3, v3, v233, v159
	global_store_dword v176, v36, s[94:95]
	global_store_dword v177, v37, s[94:95]
	global_store_dword v178, v38, s[94:95]
	global_store_dword v179, v39, s[94:95]
	global_store_dword v176, v28, s[94:95] offset:64
	global_store_dword v177, v29, s[94:95] offset:64
	global_store_dword v178, v30, s[94:95] offset:64
	global_store_dword v179, v31, s[94:95] offset:64
	global_store_dword v176, v4, s[94:95] offset:512
	global_store_dword v177, v5, s[94:95] offset:512
	global_store_dword v178, v6, s[94:95] offset:512
	global_store_dword v179, v7, s[94:95] offset:512
	global_store_dword v176, v0, s[94:95] offset:576
	global_store_dword v177, v1, s[94:95] offset:576
	global_store_dword v178, v2, s[94:95] offset:576
	global_store_dword v179, v3, s[94:95] offset:576
	v_readlane_b32 s0, v254, 1
	s_add_i32 s44, s44, s0
	s_barrier
	v_readlane_b32 s1, v254, 2
	s_cmp_ge_i32 s44, s46
	s_cbranch_scc1 .LBB0_1172
.LBB0_1166:
	s_mov_b32 s2, s44
	s_mov_b32 s3, 0
	s_mov_b32 s94, 0
	s_mov_b32 s95, 28
	s_cmpk_eq_u32 s16, 0x40
	s_cbranch_scc0 .Lgo_fz_no
	v_readlane_b32 s0, v254, 1
	s_cmpk_eq_u32 s0, 0x100
	s_cbranch_scc0 .Lgo_fz_no
	s_mov_b32 s3, 3
	s_and_b32 s0, s44, 7
	s_lshr_b32 s1, s44, 3
	s_lshr_b32 s2, s1, 5
	s_and_b32 s1, s1, 31
	s_lshl_b32 s2, s2, 5
	s_lshl_b32 s0, s0, 2
	s_add_u32 s2, s2, s0
	s_and_b32 s0, s1, 3
	s_add_u32 s2, s2, s0
	s_lshr_b32 s1, s1, 2
	s_lshl_b32 s1, s1, 3
	s_and_b32 s0, s2, 7
	s_or_b32 s1, s1, s0
	s_lshr_b32 s0, s2, 3
	s_lshl_b32 s1, s1, 3
	s_or_b32 s2, s1, s0
	s_branch .Lgo_sk_dec
.Lgo_fz_no:
	s_lshl_b32 s32, s16, 3
	s_cmp_eq_u32 s32, s46
	s_cbranch_scc1 .Lgo_sk_dec
	s_cmpk_lt_i32 s44, 0x200
	s_cbranch_scc1 .Lgo_sk_dec
	s_mov_b32 s95, 14
	s_mov_b32 s3, 1
	s_sub_u32 s32, s44, 0x200
	s_cmpk_lt_i32 s44, 0x220
	s_cbranch_scc1 .Lgo_sk_dec
	s_mov_b32 s3, 2
	s_mov_b32 s95, 10
	s_movk_i32 s94, 0x900
	s_sub_u32 s2, s44, 32
	s_sub_u32 s32, s2, 0x200

.LBB0_1277:
.Lpost_entry:
	v_readlane_b32 s40, v255, 0
	v_readlane_b32 s9, v254, 1
	s_cmp_eq_u32 s40, 1
	s_cbranch_scc0 .Lpost_go
	s_cmpk_eq_u32 s9, 0x100
	s_cbranch_scc1 .Lpost_done
